# scan pass 2 rebalanced 16/16: the heavier half of the attention q-tile pairs does no scan chunk, the lighter half does two
# speedup vs baseline: 1.0079x; 1.0026x over previous
; DEV int ltid() { int t = threadIdx.x; asm volatile("" : "+v"(t)); return t; }
; DEV void ph_scan2(const Params& p, int item) {
;   const int b = item / NCH, c = item % NCH, ch = ltid() * 4;
;   float H[4] = {0.f, 0.f, 0.f, 0.f};
;   for (int c2 = 0; c2 < c; ++c2) {
;     float4 a = *(const float4*)(p.csA + (size_t)(b * NCH + c2) * 1024 + ch);
;     float4 hh = *(const float4*)(p.csH + (size_t)(b * NCH + c2) * 1024 + ch);
;     H[0] = a.x * H[0] + hh.x; H[1] = a.y * H[1] + hh.y; H[2] = a.z * H[2] + hh.z; H[3] = a.w * H[3] + hh.w;
;   }
;   const size_t row0 = (size_t)(b * S_ + c * CHL);
; #pragma unroll 8
;   for (int t = 0; t < CHL; ++t) {
; __global__ void __launch_bounds__(256, 2) fwd_megakernel(Params p) {
;     ...
;   for (int it = bid; it < B_ * NCH; it += nb) ph_scan2(p, it);
.Lp6_entry:
	v_mov_b32_e32 v1, v0
	s_cmpk_gt_i32 s94, 0x1ff
	s_waitcnt lgkmcnt(0)
	s_barrier
	s_cbranch_scc1 .LBB0_1132
	s_mov_b64 exec, -1
	v_lshlrev_b32_e32 v1, 4, v0
	v_lshlrev_b32_e32 v2, 3, v0
	v_mov_b32_e32 v8, 0x3ba10414
	v_mov_b32_e32 v9, 0xb9c68948
	v_mov_b32_e32 v3, 0x7f800000
	s_mov_b32 s72, 0x378e98ab
	s_mov_b32 s73, 0x3b7cd369
	s_mov_b32 s74, 0xbcc618b2
	s_mov_b32 s75, 0x3dda74e4
	s_mov_b32 s76, 0x3f228afd
	s_mov_b32 s77, 0x3e03c728
	s_mov_b32 s78, 0xbfb8aa3b
	s_mov_b32 s79, 0x42ce8ed0
	s_mov_b32 s80, 0xc2b17218
	s_brev_b32 s81, -2
	s_mov_b32 s50, s94
	s_lshr_b32 s8, s94, 4
	s_cmp_gt_u32 s8, 15
	s_cbranch_scc1 .Lsc_end

; DEV unsigned pack2(float a, float b) { float2v v = {a, b}; return __builtin_bit_cast(unsigned, __builtin_convertvector(v, bf16x2v)); }
; DEV float bflo(unsigned u) { return __uint_as_float(u << 16); }
; DEV float bfhi(unsigned u) { return __uint_as_float(u & 0xffff0000u); }
; DEV float gelu_exact(float v) { return 0.5f * v * (1.f + erff(v * 0.7071067811865476f)); }
; DEV void ph_scan2(const Params& p, int item) {
;     ...
; #pragma unroll 8
;   for (int t = 0; t < CHL; ++t) {
;     float4 a = *(const float4*)(p.a_arr + (row0 + t) * 1024 + ch);
;     float4 bb = *(const float4*)(p.b_arr + (row0 + t) * 1024 + ch);
;     u32x2 xg = *(const u32x2*)(p.z + (row0 + t) * ZLD + CXG + ch);
;     H[0] = a.x * H[0] + bb.x; H[1] = a.y * H[1] + bb.y; H[2] = a.z * H[2] + bb.z; H[3] = a.w * H[3] + bb.w;
;     u32x2 pk;
;     pk[0] = pack2(gelu_exact(bflo(xg[0])) * H[0], gelu_exact(bfhi(xg[0])) * H[1]);
;     pk[1] = pack2(gelu_exact(bflo(xg[1])) * H[2], gelu_exact(bfhi(xg[1])) * H[3]);
;     *(u32x2*)(p.orn + (row0 + t) * 1024 + ch) = pk;
;   }
.Lsc_main:
	global_load_dwordx4 v[80:83], v1, s[2:3] sc0 sc1 nt
	global_load_dwordx4 v[84:87], v1, s[4:5] sc0 sc1 nt
	global_load_dwordx2 v[88:89], v2, s[6:7] sc0 sc1 nt
	s_add_u32 s2, s2, 0x1000
	s_addc_u32 s3, s3, 0
	s_add_u32 s4, s4, 0x1000
	s_addc_u32 s5, s5, 0
	s_add_u32 s6, s6, 0x2500
	s_addc_u32 s7, s7, 0
	global_load_dwordx4 v[90:93], v1, s[2:3] sc0 sc1 nt
	global_load_dwordx4 v[94:97], v1, s[4:5] sc0 sc1 nt
	global_load_dwordx2 v[98:99], v2, s[6:7] sc0 sc1 nt
	s_add_u32 s2, s2, 0x1000
	s_addc_u32 s3, s3, 0
	s_add_u32 s4, s4, 0x1000
	s_addc_u32 s5, s5, 0
	s_add_u32 s6, s6, 0x2500
	s_addc_u32 s7, s7, 0
	global_load_dwordx4 v[100:103], v1, s[2:3] sc0 sc1 nt
	global_load_dwordx4 v[104:107], v1, s[4:5] sc0 sc1 nt
	global_load_dwordx2 v[108:109], v2, s[6:7] sc0 sc1 nt
	s_add_u32 s2, s2, 0x1000
	s_addc_u32 s3, s3, 0
	s_add_u32 s4, s4, 0x1000
	s_addc_u32 s5, s5, 0
	s_add_u32 s6, s6, 0x2500
	s_addc_u32 s7, s7, 0
	global_load_dwordx4 v[110:113], v1, s[2:3] sc0 sc1 nt
	global_load_dwordx4 v[114:117], v1, s[4:5] sc0 sc1 nt
	global_load_dwordx2 v[118:119], v2, s[6:7] sc0 sc1 nt
	s_add_u32 s2, s2, 0x1000
	s_addc_u32 s3, s3, 0
	s_add_u32 s4, s4, 0x1000
	s_addc_u32 s5, s5, 0
	s_add_u32 s6, s6, 0x2500
	s_addc_u32 s7, s7, 0
	global_load_dwordx4 v[120:123], v1, s[2:3] sc0 sc1 nt
	global_load_dwordx4 v[124:127], v1, s[4:5] sc0 sc1 nt
	global_load_dwordx2 v[128:129], v2, s[6:7] sc0 sc1 nt
	s_add_u32 s2, s2, 0x1000
	s_addc_u32 s3, s3, 0
	s_add_u32 s4, s4, 0x1000
	s_addc_u32 s5, s5, 0
	s_add_u32 s6, s6, 0x2500
	s_addc_u32 s7, s7, 0
	global_load_dwordx4 v[130:133], v1, s[2:3] sc0 sc1 nt
	global_load_dwordx4 v[134:137], v1, s[4:5] sc0 sc1 nt
	global_load_dwordx2 v[138:139], v2, s[6:7] sc0 sc1 nt
	s_add_u32 s2, s2, 0x1000
	s_addc_u32 s3, s3, 0
	s_add_u32 s4, s4, 0x1000
	s_addc_u32 s5, s5, 0
	s_add_u32 s6, s6, 0x2500
	s_addc_u32 s7, s7, 0
	global_load_dwordx4 v[140:143], v1, s[2:3] sc0 sc1 nt
	global_load_dwordx4 v[144:147], v1, s[4:5] sc0 sc1 nt
	global_load_dwordx2 v[148:149], v2, s[6:7] sc0 sc1 nt
	s_add_u32 s2, s2, 0x1000
	s_addc_u32 s3, s3, 0
	s_add_u32 s4, s4, 0x1000
	s_addc_u32 s5, s5, 0
	s_add_u32 s6, s6, 0x2500
	s_addc_u32 s7, s7, 0
	global_load_dwordx4 v[150:153], v1, s[2:3] sc0 sc1 nt
	global_load_dwordx4 v[154:157], v1, s[4:5] sc0 sc1 nt
	global_load_dwordx2 v[158:159], v2, s[6:7] sc0 sc1 nt
	s_add_u32 s2, s2, 0x1000
	s_addc_u32 s3, s3, 0
	s_add_u32 s4, s4, 0x1000
	s_addc_u32 s5, s5, 0
	s_add_u32 s6, s6, 0x2500
	s_addc_u32 s7, s7, 0
	s_waitcnt vmcnt(21)
	v_fma_f32 v4, v80, v4, v84
	v_fma_f32 v5, v81, v5, v85
	v_fma_f32 v6, v82, v6, v86
	v_fma_f32 v7, v83, v7, v87
	v_lshlrev_b32_e32 v168, 16, v88
	v_and_b32_e32 v169, 0xffff0000, v88
	v_lshlrev_b32_e32 v170, 16, v89
	v_and_b32_e32 v171, 0xffff0000, v89
	v_mul_f32_e32 v160, 0x3f3504f3, v168
	v_mul_f32_e32 v161, v160, v160
	v_fmamk_f32 v162, v161, 0xba1345e1, v8
	v_fmaak_f32 v162, v161, v162, 0xbcdac9b8
	v_fmaak_f32 v162, v161, v162, 0x3de703be
	v_fmaak_f32 v162, v161, v162, 0xbec09330
	v_fmaak_f32 v161, v161, v162, 0x3e0375d0
	v_fma_f32 v165, |v160|, v161, |v160|
	v_fma_f32 v161, |v160|, s72, v9
	v_fma_f32 v161, |v160|, v161, s73
	v_fma_f32 v161, |v160|, v161, s74
	v_fma_f32 v161, |v160|, v161, s75
	v_fma_f32 v161, |v160|, v161, s76
	v_fma_f32 v161, |v160|, v161, s77
	v_fma_f32 v161, |v160|, v161, |v160|
	v_mul_f32_e32 v162, 0xbfb8aa3b, v161
	v_fma_f32 v163, v161, s78, -v162
	v_rndne_f32_e32 v164, v162
	v_fmac_f32_e32 v163, 0xb2a5705f, v161
	v_sub_f32_e32 v162, v162, v164
	v_add_f32_e32 v162, v162, v163
	v_cvt_i32_f32_e32 v163, v164
	v_exp_f32_e32 v162, v162
	v_cmp_nlt_f32_e32 vcc, s79, v161
	v_ldexp_f32 v162, v162, v163
	s_nop 0
	v_cndmask_b32_e32 v162, 0, v162, vcc
	v_cmp_ngt_f32_e32 vcc, s80, v161
	s_nop 1
	v_cndmask_b32_e32 v161, v3, v162, vcc
	v_sub_f32_e32 v166, 1.0, v161
	v_cmp_lt_f32_e64 vcc, |v160|, 1.0
	s_nop 1
	v_cndmask_b32_e32 v165, v166, v165, vcc
	v_bfi_b32 v165, s81, v165, v160
	v_mul_f32_e32 v161, 0.5, v168
	v_add_f32_e32 v165, 1.0, v165
	v_mul_f32_e32 v161, v161, v165
	v_mul_f32_e32 v176, v161, v4
	v_mul_f32_e32 v160, 0x3f3504f3, v169
	v_mul_f32_e32 v161, v160, v160
	v_fmamk_f32 v162, v161, 0xba1345e1, v8
	v_fmaak_f32 v162, v161, v162, 0xbcdac9b8
	v_fmaak_f32 v162, v161, v162, 0x3de703be
	v_fmaak_f32 v162, v161, v162, 0xbec09330
	v_fmaak_f32 v161, v161, v162, 0x3e0375d0
	v_fma_f32 v165, |v160|, v161, |v160|
	v_fma_f32 v161, |v160|, s72, v9
	v_fma_f32 v161, |v160|, v161, s73
	v_fma_f32 v161, |v160|, v161, s74
	v_fma_f32 v161, |v160|, v161, s75
	v_fma_f32 v161, |v160|, v161, s76
	v_fma_f32 v161, |v160|, v161, s77
	v_fma_f32 v161, |v160|, v161, |v160|
	v_mul_f32_e32 v162, 0xbfb8aa3b, v161
	v_fma_f32 v163, v161, s78, -v162
	v_rndne_f32_e32 v164, v162
	v_fmac_f32_e32 v163, 0xb2a5705f, v161
	v_sub_f32_e32 v162, v162, v164
	v_add_f32_e32 v162, v162, v163
	v_cvt_i32_f32_e32 v163, v164
	v_exp_f32_e32 v162, v162
	v_cmp_nlt_f32_e32 vcc, s79, v161
	v_ldexp_f32 v162, v162, v163
	s_nop 0
	v_cndmask_b32_e32 v162, 0, v162, vcc
	v_cmp_ngt_f32_e32 vcc, s80, v161
	s_nop 1
	v_cndmask_b32_e32 v161, v3, v162, vcc
	v_sub_f32_e32 v166, 1.0, v161
	v_cmp_lt_f32_e64 vcc, |v160|, 1.0
	s_nop 1
	v_cndmask_b32_e32 v165, v166, v165, vcc
	v_bfi_b32 v165, s81, v165, v160
	v_mul_f32_e32 v161, 0.5, v169
	v_add_f32_e32 v165, 1.0, v165
	v_mul_f32_e32 v161, v161, v165
	v_mul_f32_e32 v177, v161, v5
	v_mul_f32_e32 v160, 0x3f3504f3, v170
	v_mul_f32_e32 v161, v160, v160
	v_fmamk_f32 v162, v161, 0xba1345e1, v8
	v_fmaak_f32 v162, v161, v162, 0xbcdac9b8
	v_fmaak_f32 v162, v161, v162, 0x3de703be
	v_fmaak_f32 v162, v161, v162, 0xbec09330
	v_fmaak_f32 v161, v161, v162, 0x3e0375d0
	v_fma_f32 v165, |v160|, v161, |v160|
; DEV unsigned pack2(float a, float b) { float2v v = {a, b}; return __builtin_bit_cast(unsigned, __builtin_convertvector(v, bf16x2v)); }
; DEV float bflo(unsigned u) { return __uint_as_float(u << 16); }
; DEV float bfhi(unsigned u) { return __uint_as_float(u & 0xffff0000u); }
; DEV float gelu_exact(float v) { return 0.5f * v * (1.f + erff(v * 0.7071067811865476f)); }
; DEV void ph_scan2(const Params& p, int item) {
;     ...
; #pragma unroll 8
;   for (int t = 0; t < CHL; ++t) {
;     float4 a = *(const float4*)(p.a_arr + (row0 + t) * 1024 + ch);
;     float4 bb = *(const float4*)(p.b_arr + (row0 + t) * 1024 + ch);
;     u32x2 xg = *(const u32x2*)(p.z + (row0 + t) * ZLD + CXG + ch);
;     H[0] = a.x * H[0] + bb.x; H[1] = a.y * H[1] + bb.y; H[2] = a.z * H[2] + bb.z; H[3] = a.w * H[3] + bb.w;
;     u32x2 pk;
;     pk[0] = pack2(gelu_exact(bflo(xg[0])) * H[0], gelu_exact(bfhi(xg[0])) * H[1]);
;     pk[1] = pack2(gelu_exact(bflo(xg[1])) * H[2], gelu_exact(bfhi(xg[1])) * H[3]);
;     *(u32x2*)(p.orn + (row0 + t) * 1024 + ch) = pk;
;   }
	v_fma_f32 v161, |v160|, s72, v9
	v_fma_f32 v161, |v160|, v161, s73
	v_fma_f32 v161, |v160|, v161, s74
	v_fma_f32 v161, |v160|, v161, s75
	v_fma_f32 v161, |v160|, v161, s76
	v_fma_f32 v161, |v160|, v161, s77
	v_fma_f32 v161, |v160|, v161, |v160|
	v_mul_f32_e32 v162, 0xbfb8aa3b, v161
	v_fma_f32 v163, v161, s78, -v162
	v_rndne_f32_e32 v164, v162
	v_fmac_f32_e32 v163, 0xb2a5705f, v161
	v_sub_f32_e32 v162, v162, v164
	v_add_f32_e32 v162, v162, v163
	v_cvt_i32_f32_e32 v163, v164
	v_exp_f32_e32 v162, v162
	v_cmp_nlt_f32_e32 vcc, s79, v161
	v_ldexp_f32 v162, v162, v163
	s_nop 0
	v_cndmask_b32_e32 v162, 0, v162, vcc
	v_cmp_ngt_f32_e32 vcc, s80, v161
	s_nop 1
	v_cndmask_b32_e32 v161, v3, v162, vcc
	v_sub_f32_e32 v166, 1.0, v161
	v_cmp_lt_f32_e64 vcc, |v160|, 1.0
	s_nop 1
	v_cndmask_b32_e32 v165, v166, v165, vcc
	v_bfi_b32 v165, s81, v165, v160
	v_mul_f32_e32 v161, 0.5, v170
	v_add_f32_e32 v165, 1.0, v165
	v_mul_f32_e32 v161, v161, v165
	v_mul_f32_e32 v178, v161, v6
	v_mul_f32_e32 v160, 0x3f3504f3, v171
	v_mul_f32_e32 v161, v160, v160
	v_fmamk_f32 v162, v161, 0xba1345e1, v8
	v_fmaak_f32 v162, v161, v162, 0xbcdac9b8
	v_fmaak_f32 v162, v161, v162, 0x3de703be
	v_fmaak_f32 v162, v161, v162, 0xbec09330
	v_fmaak_f32 v161, v161, v162, 0x3e0375d0
	v_fma_f32 v165, |v160|, v161, |v160|
	v_fma_f32 v161, |v160|, s72, v9
	v_fma_f32 v161, |v160|, v161, s73
	v_fma_f32 v161, |v160|, v161, s74
	v_fma_f32 v161, |v160|, v161, s75
	v_fma_f32 v161, |v160|, v161, s76
	v_fma_f32 v161, |v160|, v161, s77
	v_fma_f32 v161, |v160|, v161, |v160|
	v_mul_f32_e32 v162, 0xbfb8aa3b, v161
	v_fma_f32 v163, v161, s78, -v162
	v_rndne_f32_e32 v164, v162
	v_fmac_f32_e32 v163, 0xb2a5705f, v161
	v_sub_f32_e32 v162, v162, v164
	v_add_f32_e32 v162, v162, v163
	v_cvt_i32_f32_e32 v163, v164
	v_exp_f32_e32 v162, v162
	v_cmp_nlt_f32_e32 vcc, s79, v161
	v_ldexp_f32 v162, v162, v163
	s_nop 0
	v_cndmask_b32_e32 v162, 0, v162, vcc
	v_cmp_ngt_f32_e32 vcc, s80, v161
	s_nop 1
	v_cndmask_b32_e32 v161, v3, v162, vcc
	v_sub_f32_e32 v166, 1.0, v161
	v_cmp_lt_f32_e64 vcc, |v160|, 1.0
	s_nop 1
	v_cndmask_b32_e32 v165, v166, v165, vcc
	v_bfi_b32 v165, s81, v165, v160
	v_mul_f32_e32 v161, 0.5, v171
	v_add_f32_e32 v165, 1.0, v165
	v_mul_f32_e32 v161, v161, v165
	v_mul_f32_e32 v179, v161, v7
	v_cvt_pk_bf16_f32 v180, v176, v177
	v_cvt_pk_bf16_f32 v181, v178, v179
	global_store_dwordx2 v2, v[180:181], s[34:35]
	s_add_u32 s34, s34, 0x800
	s_addc_u32 s35, s35, 0
	s_waitcnt vmcnt(19)
	v_fma_f32 v4, v90, v4, v94
	v_fma_f32 v5, v91, v5, v95
	v_fma_f32 v6, v92, v6, v96
	v_fma_f32 v7, v93, v7, v97
	v_lshlrev_b32_e32 v168, 16, v98
	v_and_b32_e32 v169, 0xffff0000, v98
	v_lshlrev_b32_e32 v170, 16, v99
	v_and_b32_e32 v171, 0xffff0000, v99
	v_mul_f32_e32 v160, 0x3f3504f3, v168
	v_mul_f32_e32 v161, v160, v160
	v_fmamk_f32 v162, v161, 0xba1345e1, v8
	v_fmaak_f32 v162, v161, v162, 0xbcdac9b8
	v_fmaak_f32 v162, v161, v162, 0x3de703be
	v_fmaak_f32 v162, v161, v162, 0xbec09330
	v_fmaak_f32 v161, v161, v162, 0x3e0375d0
	v_fma_f32 v165, |v160|, v161, |v160|
	v_fma_f32 v161, |v160|, s72, v9
	v_fma_f32 v161, |v160|, v161, s73
	v_fma_f32 v161, |v160|, v161, s74
	v_fma_f32 v161, |v160|, v161, s75
	v_fma_f32 v161, |v160|, v161, s76
	v_fma_f32 v161, |v160|, v161, s77
	v_fma_f32 v161, |v160|, v161, |v160|
	v_mul_f32_e32 v162, 0xbfb8aa3b, v161
	v_fma_f32 v163, v161, s78, -v162
	v_rndne_f32_e32 v164, v162
	v_fmac_f32_e32 v163, 0xb2a5705f, v161
	v_sub_f32_e32 v162, v162, v164
	v_add_f32_e32 v162, v162, v163
	v_cvt_i32_f32_e32 v163, v164
	v_exp_f32_e32 v162, v162
	v_cmp_nlt_f32_e32 vcc, s79, v161
	v_ldexp_f32 v162, v162, v163
	s_nop 0
	v_cndmask_b32_e32 v162, 0, v162, vcc
	v_cmp_ngt_f32_e32 vcc, s80, v161
	s_nop 1
	v_cndmask_b32_e32 v161, v3, v162, vcc
	v_sub_f32_e32 v166, 1.0, v161
	v_cmp_lt_f32_e64 vcc, |v160|, 1.0
	s_nop 1
	v_cndmask_b32_e32 v165, v166, v165, vcc
	v_bfi_b32 v165, s81, v165, v160
	v_mul_f32_e32 v161, 0.5, v168
	v_add_f32_e32 v165, 1.0, v165
	v_mul_f32_e32 v161, v161, v165
	v_mul_f32_e32 v176, v161, v4
	v_mul_f32_e32 v160, 0x3f3504f3, v169
	v_mul_f32_e32 v161, v160, v160
	v_fmamk_f32 v162, v161, 0xba1345e1, v8
	v_fmaak_f32 v162, v161, v162, 0xbcdac9b8
	v_fmaak_f32 v162, v161, v162, 0x3de703be
	v_fmaak_f32 v162, v161, v162, 0xbec09330
	v_fmaak_f32 v161, v161, v162, 0x3e0375d0
	v_fma_f32 v165, |v160|, v161, |v160|
	v_fma_f32 v161, |v160|, s72, v9
	v_fma_f32 v161, |v160|, v161, s73
	v_fma_f32 v161, |v160|, v161, s74
	v_fma_f32 v161, |v160|, v161, s75
	v_fma_f32 v161, |v160|, v161, s76
	v_fma_f32 v161, |v160|, v161, s77
	v_fma_f32 v161, |v160|, v161, |v160|
	v_mul_f32_e32 v162, 0xbfb8aa3b, v161
	v_fma_f32 v163, v161, s78, -v162
	v_rndne_f32_e32 v164, v162
	v_fmac_f32_e32 v163, 0xb2a5705f, v161
	v_sub_f32_e32 v162, v162, v164
	v_add_f32_e32 v162, v162, v163
	v_cvt_i32_f32_e32 v163, v164
	v_exp_f32_e32 v162, v162
	v_cmp_nlt_f32_e32 vcc, s79, v161
	v_ldexp_f32 v162, v162, v163
	s_nop 0
	v_cndmask_b32_e32 v162, 0, v162, vcc
	v_cmp_ngt_f32_e32 vcc, s80, v161
	s_nop 1
	v_cndmask_b32_e32 v161, v3, v162, vcc
	v_sub_f32_e32 v166, 1.0, v161
	v_cmp_lt_f32_e64 vcc, |v160|, 1.0
	s_nop 1
	v_cndmask_b32_e32 v165, v166, v165, vcc
	v_bfi_b32 v165, s81, v165, v160
	v_mul_f32_e32 v161, 0.5, v169
	v_add_f32_e32 v165, 1.0, v165
	v_mul_f32_e32 v161, v161, v165
	v_mul_f32_e32 v177, v161, v5
	v_mul_f32_e32 v160, 0x3f3504f3, v170
	v_mul_f32_e32 v161, v160, v160
	v_fmamk_f32 v162, v161, 0xba1345e1, v8
	v_fmaak_f32 v162, v161, v162, 0xbcdac9b8
	v_fmaak_f32 v162, v161, v162, 0x3de703be
	v_fmaak_f32 v162, v161, v162, 0xbec09330
	v_fmaak_f32 v161, v161, v162, 0x3e0375d0
	v_fma_f32 v165, |v160|, v161, |v160|
	v_fma_f32 v161, |v160|, s72, v9
; DEV unsigned pack2(float a, float b) { float2v v = {a, b}; return __builtin_bit_cast(unsigned, __builtin_convertvector(v, bf16x2v)); }
; DEV float bflo(unsigned u) { return __uint_as_float(u << 16); }
; DEV float bfhi(unsigned u) { return __uint_as_float(u & 0xffff0000u); }
; DEV float gelu_exact(float v) { return 0.5f * v * (1.f + erff(v * 0.7071067811865476f)); }
; DEV void ph_scan2(const Params& p, int item) {
;     ...
; #pragma unroll 8
;   for (int t = 0; t < CHL; ++t) {
;     float4 a = *(const float4*)(p.a_arr + (row0 + t) * 1024 + ch);
;     float4 bb = *(const float4*)(p.b_arr + (row0 + t) * 1024 + ch);
;     u32x2 xg = *(const u32x2*)(p.z + (row0 + t) * ZLD + CXG + ch);
;     H[0] = a.x * H[0] + bb.x; H[1] = a.y * H[1] + bb.y; H[2] = a.z * H[2] + bb.z; H[3] = a.w * H[3] + bb.w;
;     u32x2 pk;
;     pk[0] = pack2(gelu_exact(bflo(xg[0])) * H[0], gelu_exact(bfhi(xg[0])) * H[1]);
;     pk[1] = pack2(gelu_exact(bflo(xg[1])) * H[2], gelu_exact(bfhi(xg[1])) * H[3]);
;     *(u32x2*)(p.orn + (row0 + t) * 1024 + ch) = pk;
;   }
	v_fma_f32 v161, |v160|, v161, s73
	v_fma_f32 v161, |v160|, v161, s74
	v_fma_f32 v161, |v160|, v161, s75
	v_fma_f32 v161, |v160|, v161, s76
	v_fma_f32 v161, |v160|, v161, s77
	v_fma_f32 v161, |v160|, v161, |v160|
	v_mul_f32_e32 v162, 0xbfb8aa3b, v161
	v_fma_f32 v163, v161, s78, -v162
	v_rndne_f32_e32 v164, v162
	v_fmac_f32_e32 v163, 0xb2a5705f, v161
	v_sub_f32_e32 v162, v162, v164
	v_add_f32_e32 v162, v162, v163
	v_cvt_i32_f32_e32 v163, v164
	v_exp_f32_e32 v162, v162
	v_cmp_nlt_f32_e32 vcc, s79, v161
	v_ldexp_f32 v162, v162, v163
	s_nop 0
	v_cndmask_b32_e32 v162, 0, v162, vcc
	v_cmp_ngt_f32_e32 vcc, s80, v161
	s_nop 1
	v_cndmask_b32_e32 v161, v3, v162, vcc
	v_sub_f32_e32 v166, 1.0, v161
	v_cmp_lt_f32_e64 vcc, |v160|, 1.0
	s_nop 1
	v_cndmask_b32_e32 v165, v166, v165, vcc
	v_bfi_b32 v165, s81, v165, v160
	v_mul_f32_e32 v161, 0.5, v170
	v_add_f32_e32 v165, 1.0, v165
	v_mul_f32_e32 v161, v161, v165
	v_mul_f32_e32 v178, v161, v6
	v_mul_f32_e32 v160, 0x3f3504f3, v171
	v_mul_f32_e32 v161, v160, v160
	v_fmamk_f32 v162, v161, 0xba1345e1, v8
	v_fmaak_f32 v162, v161, v162, 0xbcdac9b8
	v_fmaak_f32 v162, v161, v162, 0x3de703be
	v_fmaak_f32 v162, v161, v162, 0xbec09330
	v_fmaak_f32 v161, v161, v162, 0x3e0375d0
	v_fma_f32 v165, |v160|, v161, |v160|
	v_fma_f32 v161, |v160|, s72, v9
	v_fma_f32 v161, |v160|, v161, s73
	v_fma_f32 v161, |v160|, v161, s74
	v_fma_f32 v161, |v160|, v161, s75
	v_fma_f32 v161, |v160|, v161, s76
	v_fma_f32 v161, |v160|, v161, s77
	v_fma_f32 v161, |v160|, v161, |v160|
	v_mul_f32_e32 v162, 0xbfb8aa3b, v161
	v_fma_f32 v163, v161, s78, -v162
	v_rndne_f32_e32 v164, v162
	v_fmac_f32_e32 v163, 0xb2a5705f, v161
	v_sub_f32_e32 v162, v162, v164
	v_add_f32_e32 v162, v162, v163
	v_cvt_i32_f32_e32 v163, v164
	v_exp_f32_e32 v162, v162
	v_cmp_nlt_f32_e32 vcc, s79, v161
	v_ldexp_f32 v162, v162, v163
	s_nop 0
	v_cndmask_b32_e32 v162, 0, v162, vcc
	v_cmp_ngt_f32_e32 vcc, s80, v161
	s_nop 1
	v_cndmask_b32_e32 v161, v3, v162, vcc
	v_sub_f32_e32 v166, 1.0, v161
	v_cmp_lt_f32_e64 vcc, |v160|, 1.0
	s_nop 1
	v_cndmask_b32_e32 v165, v166, v165, vcc
	v_bfi_b32 v165, s81, v165, v160
	v_mul_f32_e32 v161, 0.5, v171
	v_add_f32_e32 v165, 1.0, v165
	v_mul_f32_e32 v161, v161, v165
	v_mul_f32_e32 v179, v161, v7
	v_cvt_pk_bf16_f32 v180, v176, v177
	v_cvt_pk_bf16_f32 v181, v178, v179
	global_store_dwordx2 v2, v[180:181], s[34:35]
	s_add_u32 s34, s34, 0x800
	s_addc_u32 s35, s35, 0
	s_waitcnt vmcnt(17)
	v_fma_f32 v4, v100, v4, v104
	v_fma_f32 v5, v101, v5, v105
	v_fma_f32 v6, v102, v6, v106
	v_fma_f32 v7, v103, v7, v107
	v_lshlrev_b32_e32 v168, 16, v108
	v_and_b32_e32 v169, 0xffff0000, v108
	v_lshlrev_b32_e32 v170, 16, v109
	v_and_b32_e32 v171, 0xffff0000, v109
	v_mul_f32_e32 v160, 0x3f3504f3, v168
	v_mul_f32_e32 v161, v160, v160
	v_fmamk_f32 v162, v161, 0xba1345e1, v8
	v_fmaak_f32 v162, v161, v162, 0xbcdac9b8
	v_fmaak_f32 v162, v161, v162, 0x3de703be
	v_fmaak_f32 v162, v161, v162, 0xbec09330
	v_fmaak_f32 v161, v161, v162, 0x3e0375d0
	v_fma_f32 v165, |v160|, v161, |v160|
	v_fma_f32 v161, |v160|, s72, v9
	v_fma_f32 v161, |v160|, v161, s73
	v_fma_f32 v161, |v160|, v161, s74
	v_fma_f32 v161, |v160|, v161, s75
	v_fma_f32 v161, |v160|, v161, s76
	v_fma_f32 v161, |v160|, v161, s77
	v_fma_f32 v161, |v160|, v161, |v160|
	v_mul_f32_e32 v162, 0xbfb8aa3b, v161
	v_fma_f32 v163, v161, s78, -v162
	v_rndne_f32_e32 v164, v162
	v_fmac_f32_e32 v163, 0xb2a5705f, v161
	v_sub_f32_e32 v162, v162, v164
	v_add_f32_e32 v162, v162, v163
	v_cvt_i32_f32_e32 v163, v164
	v_exp_f32_e32 v162, v162
	v_cmp_nlt_f32_e32 vcc, s79, v161
	v_ldexp_f32 v162, v162, v163
	s_nop 0
	v_cndmask_b32_e32 v162, 0, v162, vcc
	v_cmp_ngt_f32_e32 vcc, s80, v161
	s_nop 1
	v_cndmask_b32_e32 v161, v3, v162, vcc
	v_sub_f32_e32 v166, 1.0, v161
	v_cmp_lt_f32_e64 vcc, |v160|, 1.0
	s_nop 1
	v_cndmask_b32_e32 v165, v166, v165, vcc
	v_bfi_b32 v165, s81, v165, v160
	v_mul_f32_e32 v161, 0.5, v168
	v_add_f32_e32 v165, 1.0, v165
	v_mul_f32_e32 v161, v161, v165
	v_mul_f32_e32 v176, v161, v4
	v_mul_f32_e32 v160, 0x3f3504f3, v169
	v_mul_f32_e32 v161, v160, v160
	v_fmamk_f32 v162, v161, 0xba1345e1, v8
	v_fmaak_f32 v162, v161, v162, 0xbcdac9b8
	v_fmaak_f32 v162, v161, v162, 0x3de703be
	v_fmaak_f32 v162, v161, v162, 0xbec09330
	v_fmaak_f32 v161, v161, v162, 0x3e0375d0
	v_fma_f32 v165, |v160|, v161, |v160|
	v_fma_f32 v161, |v160|, s72, v9
	v_fma_f32 v161, |v160|, v161, s73
	v_fma_f32 v161, |v160|, v161, s74
	v_fma_f32 v161, |v160|, v161, s75
	v_fma_f32 v161, |v160|, v161, s76
	v_fma_f32 v161, |v160|, v161, s77
	v_fma_f32 v161, |v160|, v161, |v160|
	v_mul_f32_e32 v162, 0xbfb8aa3b, v161
	v_fma_f32 v163, v161, s78, -v162
	v_rndne_f32_e32 v164, v162
	v_fmac_f32_e32 v163, 0xb2a5705f, v161
	v_sub_f32_e32 v162, v162, v164
	v_add_f32_e32 v162, v162, v163
	v_cvt_i32_f32_e32 v163, v164
	v_exp_f32_e32 v162, v162
	v_cmp_nlt_f32_e32 vcc, s79, v161
	v_ldexp_f32 v162, v162, v163
	s_nop 0
	v_cndmask_b32_e32 v162, 0, v162, vcc
	v_cmp_ngt_f32_e32 vcc, s80, v161
	s_nop 1
	v_cndmask_b32_e32 v161, v3, v162, vcc
	v_sub_f32_e32 v166, 1.0, v161
	v_cmp_lt_f32_e64 vcc, |v160|, 1.0
	s_nop 1
	v_cndmask_b32_e32 v165, v166, v165, vcc
	v_bfi_b32 v165, s81, v165, v160
	v_mul_f32_e32 v161, 0.5, v169
	v_add_f32_e32 v165, 1.0, v165
	v_mul_f32_e32 v161, v161, v165
	v_mul_f32_e32 v177, v161, v5
	v_mul_f32_e32 v160, 0x3f3504f3, v170
	v_mul_f32_e32 v161, v160, v160
	v_fmamk_f32 v162, v161, 0xba1345e1, v8
	v_fmaak_f32 v162, v161, v162, 0xbcdac9b8
	v_fmaak_f32 v162, v161, v162, 0x3de703be
	v_fmaak_f32 v162, v161, v162, 0xbec09330
	v_fmaak_f32 v161, v161, v162, 0x3e0375d0
	v_fma_f32 v165, |v160|, v161, |v160|
	v_fma_f32 v161, |v160|, s72, v9
	v_fma_f32 v161, |v160|, v161, s73
; DEV unsigned pack2(float a, float b) { float2v v = {a, b}; return __builtin_bit_cast(unsigned, __builtin_convertvector(v, bf16x2v)); }
; DEV float bflo(unsigned u) { return __uint_as_float(u << 16); }
; DEV float bfhi(unsigned u) { return __uint_as_float(u & 0xffff0000u); }
; DEV float gelu_exact(float v) { return 0.5f * v * (1.f + erff(v * 0.7071067811865476f)); }
; DEV void ph_scan2(const Params& p, int item) {
;     ...
; #pragma unroll 8
;   for (int t = 0; t < CHL; ++t) {
;     float4 a = *(const float4*)(p.a_arr + (row0 + t) * 1024 + ch);
;     float4 bb = *(const float4*)(p.b_arr + (row0 + t) * 1024 + ch);
;     u32x2 xg = *(const u32x2*)(p.z + (row0 + t) * ZLD + CXG + ch);
;     H[0] = a.x * H[0] + bb.x; H[1] = a.y * H[1] + bb.y; H[2] = a.z * H[2] + bb.z; H[3] = a.w * H[3] + bb.w;
;     u32x2 pk;
;     pk[0] = pack2(gelu_exact(bflo(xg[0])) * H[0], gelu_exact(bfhi(xg[0])) * H[1]);
;     pk[1] = pack2(gelu_exact(bflo(xg[1])) * H[2], gelu_exact(bfhi(xg[1])) * H[3]);
;     *(u32x2*)(p.orn + (row0 + t) * 1024 + ch) = pk;
;   }
	v_fma_f32 v161, |v160|, v161, s74
	v_fma_f32 v161, |v160|, v161, s75
	v_fma_f32 v161, |v160|, v161, s76
	v_fma_f32 v161, |v160|, v161, s77
	v_fma_f32 v161, |v160|, v161, |v160|
	v_mul_f32_e32 v162, 0xbfb8aa3b, v161
	v_fma_f32 v163, v161, s78, -v162
	v_rndne_f32_e32 v164, v162
	v_fmac_f32_e32 v163, 0xb2a5705f, v161
	v_sub_f32_e32 v162, v162, v164
	v_add_f32_e32 v162, v162, v163
	v_cvt_i32_f32_e32 v163, v164
	v_exp_f32_e32 v162, v162
	v_cmp_nlt_f32_e32 vcc, s79, v161
	v_ldexp_f32 v162, v162, v163
	s_nop 0
	v_cndmask_b32_e32 v162, 0, v162, vcc
	v_cmp_ngt_f32_e32 vcc, s80, v161
	s_nop 1
	v_cndmask_b32_e32 v161, v3, v162, vcc
	v_sub_f32_e32 v166, 1.0, v161
	v_cmp_lt_f32_e64 vcc, |v160|, 1.0
	s_nop 1
	v_cndmask_b32_e32 v165, v166, v165, vcc
	v_bfi_b32 v165, s81, v165, v160
	v_mul_f32_e32 v161, 0.5, v170
	v_add_f32_e32 v165, 1.0, v165
	v_mul_f32_e32 v161, v161, v165
	v_mul_f32_e32 v178, v161, v6
	v_mul_f32_e32 v160, 0x3f3504f3, v171
	v_mul_f32_e32 v161, v160, v160
	v_fmamk_f32 v162, v161, 0xba1345e1, v8
	v_fmaak_f32 v162, v161, v162, 0xbcdac9b8
	v_fmaak_f32 v162, v161, v162, 0x3de703be
	v_fmaak_f32 v162, v161, v162, 0xbec09330
	v_fmaak_f32 v161, v161, v162, 0x3e0375d0
	v_fma_f32 v165, |v160|, v161, |v160|
	v_fma_f32 v161, |v160|, s72, v9
	v_fma_f32 v161, |v160|, v161, s73
	v_fma_f32 v161, |v160|, v161, s74
	v_fma_f32 v161, |v160|, v161, s75
	v_fma_f32 v161, |v160|, v161, s76
	v_fma_f32 v161, |v160|, v161, s77
	v_fma_f32 v161, |v160|, v161, |v160|
	v_mul_f32_e32 v162, 0xbfb8aa3b, v161
	v_fma_f32 v163, v161, s78, -v162
	v_rndne_f32_e32 v164, v162
	v_fmac_f32_e32 v163, 0xb2a5705f, v161
	v_sub_f32_e32 v162, v162, v164
	v_add_f32_e32 v162, v162, v163
	v_cvt_i32_f32_e32 v163, v164
	v_exp_f32_e32 v162, v162
	v_cmp_nlt_f32_e32 vcc, s79, v161
	v_ldexp_f32 v162, v162, v163
	s_nop 0
	v_cndmask_b32_e32 v162, 0, v162, vcc
	v_cmp_ngt_f32_e32 vcc, s80, v161
	s_nop 1
	v_cndmask_b32_e32 v161, v3, v162, vcc
	v_sub_f32_e32 v166, 1.0, v161
	v_cmp_lt_f32_e64 vcc, |v160|, 1.0
	s_nop 1
	v_cndmask_b32_e32 v165, v166, v165, vcc
	v_bfi_b32 v165, s81, v165, v160
	v_mul_f32_e32 v161, 0.5, v171
	v_add_f32_e32 v165, 1.0, v165
	v_mul_f32_e32 v161, v161, v165
	v_mul_f32_e32 v179, v161, v7
	v_cvt_pk_bf16_f32 v180, v176, v177
	v_cvt_pk_bf16_f32 v181, v178, v179
	global_store_dwordx2 v2, v[180:181], s[34:35]
	s_add_u32 s34, s34, 0x800
	s_addc_u32 s35, s35, 0
	s_waitcnt vmcnt(15)
	v_fma_f32 v4, v110, v4, v114
	v_fma_f32 v5, v111, v5, v115
	v_fma_f32 v6, v112, v6, v116
	v_fma_f32 v7, v113, v7, v117
	v_lshlrev_b32_e32 v168, 16, v118
	v_and_b32_e32 v169, 0xffff0000, v118
	v_lshlrev_b32_e32 v170, 16, v119
	v_and_b32_e32 v171, 0xffff0000, v119
	v_mul_f32_e32 v160, 0x3f3504f3, v168
	v_mul_f32_e32 v161, v160, v160
	v_fmamk_f32 v162, v161, 0xba1345e1, v8
	v_fmaak_f32 v162, v161, v162, 0xbcdac9b8
	v_fmaak_f32 v162, v161, v162, 0x3de703be
	v_fmaak_f32 v162, v161, v162, 0xbec09330
	v_fmaak_f32 v161, v161, v162, 0x3e0375d0
	v_fma_f32 v165, |v160|, v161, |v160|
	v_fma_f32 v161, |v160|, s72, v9
	v_fma_f32 v161, |v160|, v161, s73
	v_fma_f32 v161, |v160|, v161, s74
	v_fma_f32 v161, |v160|, v161, s75
	v_fma_f32 v161, |v160|, v161, s76
	v_fma_f32 v161, |v160|, v161, s77
	v_fma_f32 v161, |v160|, v161, |v160|
	v_mul_f32_e32 v162, 0xbfb8aa3b, v161
	v_fma_f32 v163, v161, s78, -v162
	v_rndne_f32_e32 v164, v162
	v_fmac_f32_e32 v163, 0xb2a5705f, v161
	v_sub_f32_e32 v162, v162, v164
	v_add_f32_e32 v162, v162, v163
	v_cvt_i32_f32_e32 v163, v164
	v_exp_f32_e32 v162, v162
	v_cmp_nlt_f32_e32 vcc, s79, v161
	v_ldexp_f32 v162, v162, v163
	s_nop 0
	v_cndmask_b32_e32 v162, 0, v162, vcc
	v_cmp_ngt_f32_e32 vcc, s80, v161
	s_nop 1
	v_cndmask_b32_e32 v161, v3, v162, vcc
	v_sub_f32_e32 v166, 1.0, v161
	v_cmp_lt_f32_e64 vcc, |v160|, 1.0
	s_nop 1
	v_cndmask_b32_e32 v165, v166, v165, vcc
	v_bfi_b32 v165, s81, v165, v160
	v_mul_f32_e32 v161, 0.5, v168
	v_add_f32_e32 v165, 1.0, v165
	v_mul_f32_e32 v161, v161, v165
	v_mul_f32_e32 v176, v161, v4
	v_mul_f32_e32 v160, 0x3f3504f3, v169
	v_mul_f32_e32 v161, v160, v160
	v_fmamk_f32 v162, v161, 0xba1345e1, v8
	v_fmaak_f32 v162, v161, v162, 0xbcdac9b8
	v_fmaak_f32 v162, v161, v162, 0x3de703be
	v_fmaak_f32 v162, v161, v162, 0xbec09330
	v_fmaak_f32 v161, v161, v162, 0x3e0375d0
	v_fma_f32 v165, |v160|, v161, |v160|
	v_fma_f32 v161, |v160|, s72, v9
	v_fma_f32 v161, |v160|, v161, s73
	v_fma_f32 v161, |v160|, v161, s74
	v_fma_f32 v161, |v160|, v161, s75
	v_fma_f32 v161, |v160|, v161, s76
	v_fma_f32 v161, |v160|, v161, s77
	v_fma_f32 v161, |v160|, v161, |v160|
	v_mul_f32_e32 v162, 0xbfb8aa3b, v161
	v_fma_f32 v163, v161, s78, -v162
	v_rndne_f32_e32 v164, v162
	v_fmac_f32_e32 v163, 0xb2a5705f, v161
	v_sub_f32_e32 v162, v162, v164
	v_add_f32_e32 v162, v162, v163
	v_cvt_i32_f32_e32 v163, v164
	v_exp_f32_e32 v162, v162
	v_cmp_nlt_f32_e32 vcc, s79, v161
	v_ldexp_f32 v162, v162, v163
	s_nop 0
	v_cndmask_b32_e32 v162, 0, v162, vcc
	v_cmp_ngt_f32_e32 vcc, s80, v161
	s_nop 1
	v_cndmask_b32_e32 v161, v3, v162, vcc
	v_sub_f32_e32 v166, 1.0, v161
	v_cmp_lt_f32_e64 vcc, |v160|, 1.0
	s_nop 1
	v_cndmask_b32_e32 v165, v166, v165, vcc
	v_bfi_b32 v165, s81, v165, v160
	v_mul_f32_e32 v161, 0.5, v169
	v_add_f32_e32 v165, 1.0, v165
	v_mul_f32_e32 v161, v161, v165
	v_mul_f32_e32 v177, v161, v5
	v_mul_f32_e32 v160, 0x3f3504f3, v170
	v_mul_f32_e32 v161, v160, v160
	v_fmamk_f32 v162, v161, 0xba1345e1, v8
	v_fmaak_f32 v162, v161, v162, 0xbcdac9b8
	v_fmaak_f32 v162, v161, v162, 0x3de703be
	v_fmaak_f32 v162, v161, v162, 0xbec09330
	v_fmaak_f32 v161, v161, v162, 0x3e0375d0
	v_fma_f32 v165, |v160|, v161, |v160|
	v_fma_f32 v161, |v160|, s72, v9
	v_fma_f32 v161, |v160|, v161, s73
	v_fma_f32 v161, |v160|, v161, s74
; DEV unsigned pack2(float a, float b) { float2v v = {a, b}; return __builtin_bit_cast(unsigned, __builtin_convertvector(v, bf16x2v)); }
; DEV float bflo(unsigned u) { return __uint_as_float(u << 16); }
; DEV float bfhi(unsigned u) { return __uint_as_float(u & 0xffff0000u); }
; DEV float gelu_exact(float v) { return 0.5f * v * (1.f + erff(v * 0.7071067811865476f)); }
; DEV void ph_scan2(const Params& p, int item) {
;     ...
; #pragma unroll 8
;   for (int t = 0; t < CHL; ++t) {
;     float4 a = *(const float4*)(p.a_arr + (row0 + t) * 1024 + ch);
;     float4 bb = *(const float4*)(p.b_arr + (row0 + t) * 1024 + ch);
;     u32x2 xg = *(const u32x2*)(p.z + (row0 + t) * ZLD + CXG + ch);
;     H[0] = a.x * H[0] + bb.x; H[1] = a.y * H[1] + bb.y; H[2] = a.z * H[2] + bb.z; H[3] = a.w * H[3] + bb.w;
;     u32x2 pk;
;     pk[0] = pack2(gelu_exact(bflo(xg[0])) * H[0], gelu_exact(bfhi(xg[0])) * H[1]);
;     pk[1] = pack2(gelu_exact(bflo(xg[1])) * H[2], gelu_exact(bfhi(xg[1])) * H[3]);
;     *(u32x2*)(p.orn + (row0 + t) * 1024 + ch) = pk;
;   }
	v_fma_f32 v161, |v160|, v161, s75
	v_fma_f32 v161, |v160|, v161, s76
	v_fma_f32 v161, |v160|, v161, s77
	v_fma_f32 v161, |v160|, v161, |v160|
	v_mul_f32_e32 v162, 0xbfb8aa3b, v161
	v_fma_f32 v163, v161, s78, -v162
	v_rndne_f32_e32 v164, v162
	v_fmac_f32_e32 v163, 0xb2a5705f, v161
	v_sub_f32_e32 v162, v162, v164
	v_add_f32_e32 v162, v162, v163
	v_cvt_i32_f32_e32 v163, v164
	v_exp_f32_e32 v162, v162
	v_cmp_nlt_f32_e32 vcc, s79, v161
	v_ldexp_f32 v162, v162, v163
	s_nop 0
	v_cndmask_b32_e32 v162, 0, v162, vcc
	v_cmp_ngt_f32_e32 vcc, s80, v161
	s_nop 1
	v_cndmask_b32_e32 v161, v3, v162, vcc
	v_sub_f32_e32 v166, 1.0, v161
	v_cmp_lt_f32_e64 vcc, |v160|, 1.0
	s_nop 1
	v_cndmask_b32_e32 v165, v166, v165, vcc
	v_bfi_b32 v165, s81, v165, v160
	v_mul_f32_e32 v161, 0.5, v170
	v_add_f32_e32 v165, 1.0, v165
	v_mul_f32_e32 v161, v161, v165
	v_mul_f32_e32 v178, v161, v6
	v_mul_f32_e32 v160, 0x3f3504f3, v171
	v_mul_f32_e32 v161, v160, v160
	v_fmamk_f32 v162, v161, 0xba1345e1, v8
	v_fmaak_f32 v162, v161, v162, 0xbcdac9b8
	v_fmaak_f32 v162, v161, v162, 0x3de703be
	v_fmaak_f32 v162, v161, v162, 0xbec09330
	v_fmaak_f32 v161, v161, v162, 0x3e0375d0
	v_fma_f32 v165, |v160|, v161, |v160|
	v_fma_f32 v161, |v160|, s72, v9
	v_fma_f32 v161, |v160|, v161, s73
	v_fma_f32 v161, |v160|, v161, s74
	v_fma_f32 v161, |v160|, v161, s75
	v_fma_f32 v161, |v160|, v161, s76
	v_fma_f32 v161, |v160|, v161, s77
	v_fma_f32 v161, |v160|, v161, |v160|
	v_mul_f32_e32 v162, 0xbfb8aa3b, v161
	v_fma_f32 v163, v161, s78, -v162
	v_rndne_f32_e32 v164, v162
	v_fmac_f32_e32 v163, 0xb2a5705f, v161
	v_sub_f32_e32 v162, v162, v164
	v_add_f32_e32 v162, v162, v163
	v_cvt_i32_f32_e32 v163, v164
	v_exp_f32_e32 v162, v162
	v_cmp_nlt_f32_e32 vcc, s79, v161
	v_ldexp_f32 v162, v162, v163
	s_nop 0
	v_cndmask_b32_e32 v162, 0, v162, vcc
	v_cmp_ngt_f32_e32 vcc, s80, v161
	s_nop 1
	v_cndmask_b32_e32 v161, v3, v162, vcc
	v_sub_f32_e32 v166, 1.0, v161
	v_cmp_lt_f32_e64 vcc, |v160|, 1.0
	s_nop 1
	v_cndmask_b32_e32 v165, v166, v165, vcc
	v_bfi_b32 v165, s81, v165, v160
	v_mul_f32_e32 v161, 0.5, v171
	v_add_f32_e32 v165, 1.0, v165
	v_mul_f32_e32 v161, v161, v165
	v_mul_f32_e32 v179, v161, v7
	v_cvt_pk_bf16_f32 v180, v176, v177
	v_cvt_pk_bf16_f32 v181, v178, v179
	global_store_dwordx2 v2, v[180:181], s[34:35]
	s_add_u32 s34, s34, 0x800
	s_addc_u32 s35, s35, 0
	s_waitcnt vmcnt(13)
	v_fma_f32 v4, v120, v4, v124
	v_fma_f32 v5, v121, v5, v125
	v_fma_f32 v6, v122, v6, v126
	v_fma_f32 v7, v123, v7, v127
	v_lshlrev_b32_e32 v168, 16, v128
	v_and_b32_e32 v169, 0xffff0000, v128
	v_lshlrev_b32_e32 v170, 16, v129
	v_and_b32_e32 v171, 0xffff0000, v129
	v_mul_f32_e32 v160, 0x3f3504f3, v168
	v_mul_f32_e32 v161, v160, v160
	v_fmamk_f32 v162, v161, 0xba1345e1, v8
	v_fmaak_f32 v162, v161, v162, 0xbcdac9b8
	v_fmaak_f32 v162, v161, v162, 0x3de703be
	v_fmaak_f32 v162, v161, v162, 0xbec09330
	v_fmaak_f32 v161, v161, v162, 0x3e0375d0
	v_fma_f32 v165, |v160|, v161, |v160|
	v_fma_f32 v161, |v160|, s72, v9
	v_fma_f32 v161, |v160|, v161, s73
	v_fma_f32 v161, |v160|, v161, s74
	v_fma_f32 v161, |v160|, v161, s75
	v_fma_f32 v161, |v160|, v161, s76
	v_fma_f32 v161, |v160|, v161, s77
	v_fma_f32 v161, |v160|, v161, |v160|
	v_mul_f32_e32 v162, 0xbfb8aa3b, v161
	v_fma_f32 v163, v161, s78, -v162
	v_rndne_f32_e32 v164, v162
	v_fmac_f32_e32 v163, 0xb2a5705f, v161
	v_sub_f32_e32 v162, v162, v164
	v_add_f32_e32 v162, v162, v163
	v_cvt_i32_f32_e32 v163, v164
	v_exp_f32_e32 v162, v162
	v_cmp_nlt_f32_e32 vcc, s79, v161
	v_ldexp_f32 v162, v162, v163
	s_nop 0
	v_cndmask_b32_e32 v162, 0, v162, vcc
	v_cmp_ngt_f32_e32 vcc, s80, v161
	s_nop 1
	v_cndmask_b32_e32 v161, v3, v162, vcc
	v_sub_f32_e32 v166, 1.0, v161
	v_cmp_lt_f32_e64 vcc, |v160|, 1.0
	s_nop 1
	v_cndmask_b32_e32 v165, v166, v165, vcc
	v_bfi_b32 v165, s81, v165, v160
	v_mul_f32_e32 v161, 0.5, v168
	v_add_f32_e32 v165, 1.0, v165
	v_mul_f32_e32 v161, v161, v165
	v_mul_f32_e32 v176, v161, v4
	v_mul_f32_e32 v160, 0x3f3504f3, v169
	v_mul_f32_e32 v161, v160, v160
	v_fmamk_f32 v162, v161, 0xba1345e1, v8
	v_fmaak_f32 v162, v161, v162, 0xbcdac9b8
	v_fmaak_f32 v162, v161, v162, 0x3de703be
	v_fmaak_f32 v162, v161, v162, 0xbec09330
	v_fmaak_f32 v161, v161, v162, 0x3e0375d0
	v_fma_f32 v165, |v160|, v161, |v160|
	v_fma_f32 v161, |v160|, s72, v9
	v_fma_f32 v161, |v160|, v161, s73
	v_fma_f32 v161, |v160|, v161, s74
	v_fma_f32 v161, |v160|, v161, s75
	v_fma_f32 v161, |v160|, v161, s76
	v_fma_f32 v161, |v160|, v161, s77
	v_fma_f32 v161, |v160|, v161, |v160|
	v_mul_f32_e32 v162, 0xbfb8aa3b, v161
	v_fma_f32 v163, v161, s78, -v162
	v_rndne_f32_e32 v164, v162
	v_fmac_f32_e32 v163, 0xb2a5705f, v161
	v_sub_f32_e32 v162, v162, v164
	v_add_f32_e32 v162, v162, v163
	v_cvt_i32_f32_e32 v163, v164
	v_exp_f32_e32 v162, v162
	v_cmp_nlt_f32_e32 vcc, s79, v161
	v_ldexp_f32 v162, v162, v163
	s_nop 0
	v_cndmask_b32_e32 v162, 0, v162, vcc
	v_cmp_ngt_f32_e32 vcc, s80, v161
	s_nop 1
	v_cndmask_b32_e32 v161, v3, v162, vcc
	v_sub_f32_e32 v166, 1.0, v161
	v_cmp_lt_f32_e64 vcc, |v160|, 1.0
	s_nop 1
	v_cndmask_b32_e32 v165, v166, v165, vcc
	v_bfi_b32 v165, s81, v165, v160
	v_mul_f32_e32 v161, 0.5, v169
	v_add_f32_e32 v165, 1.0, v165
	v_mul_f32_e32 v161, v161, v165
	v_mul_f32_e32 v177, v161, v5
	v_mul_f32_e32 v160, 0x3f3504f3, v170
	v_mul_f32_e32 v161, v160, v160
	v_fmamk_f32 v162, v161, 0xba1345e1, v8
	v_fmaak_f32 v162, v161, v162, 0xbcdac9b8
	v_fmaak_f32 v162, v161, v162, 0x3de703be
	v_fmaak_f32 v162, v161, v162, 0xbec09330
	v_fmaak_f32 v161, v161, v162, 0x3e0375d0
	v_fma_f32 v165, |v160|, v161, |v160|
	v_fma_f32 v161, |v160|, s72, v9
	v_fma_f32 v161, |v160|, v161, s73
	v_fma_f32 v161, |v160|, v161, s74
	v_fma_f32 v161, |v160|, v161, s75
; DEV unsigned pack2(float a, float b) { float2v v = {a, b}; return __builtin_bit_cast(unsigned, __builtin_convertvector(v, bf16x2v)); }
; DEV float bflo(unsigned u) { return __uint_as_float(u << 16); }
; DEV float bfhi(unsigned u) { return __uint_as_float(u & 0xffff0000u); }
; DEV float gelu_exact(float v) { return 0.5f * v * (1.f + erff(v * 0.7071067811865476f)); }
; DEV void ph_scan2(const Params& p, int item) {
;     ...
; #pragma unroll 8
;   for (int t = 0; t < CHL; ++t) {
;     float4 a = *(const float4*)(p.a_arr + (row0 + t) * 1024 + ch);
;     float4 bb = *(const float4*)(p.b_arr + (row0 + t) * 1024 + ch);
;     u32x2 xg = *(const u32x2*)(p.z + (row0 + t) * ZLD + CXG + ch);
;     H[0] = a.x * H[0] + bb.x; H[1] = a.y * H[1] + bb.y; H[2] = a.z * H[2] + bb.z; H[3] = a.w * H[3] + bb.w;
;     u32x2 pk;
;     pk[0] = pack2(gelu_exact(bflo(xg[0])) * H[0], gelu_exact(bfhi(xg[0])) * H[1]);
;     pk[1] = pack2(gelu_exact(bflo(xg[1])) * H[2], gelu_exact(bfhi(xg[1])) * H[3]);
;     *(u32x2*)(p.orn + (row0 + t) * 1024 + ch) = pk;
;   }
	v_fma_f32 v161, |v160|, v161, s76
	v_fma_f32 v161, |v160|, v161, s77
	v_fma_f32 v161, |v160|, v161, |v160|
	v_mul_f32_e32 v162, 0xbfb8aa3b, v161
	v_fma_f32 v163, v161, s78, -v162
	v_rndne_f32_e32 v164, v162
	v_fmac_f32_e32 v163, 0xb2a5705f, v161
	v_sub_f32_e32 v162, v162, v164
	v_add_f32_e32 v162, v162, v163
	v_cvt_i32_f32_e32 v163, v164
	v_exp_f32_e32 v162, v162
	v_cmp_nlt_f32_e32 vcc, s79, v161
	v_ldexp_f32 v162, v162, v163
	s_nop 0
	v_cndmask_b32_e32 v162, 0, v162, vcc
	v_cmp_ngt_f32_e32 vcc, s80, v161
	s_nop 1
	v_cndmask_b32_e32 v161, v3, v162, vcc
	v_sub_f32_e32 v166, 1.0, v161
	v_cmp_lt_f32_e64 vcc, |v160|, 1.0
	s_nop 1
	v_cndmask_b32_e32 v165, v166, v165, vcc
	v_bfi_b32 v165, s81, v165, v160
	v_mul_f32_e32 v161, 0.5, v170
	v_add_f32_e32 v165, 1.0, v165
	v_mul_f32_e32 v161, v161, v165
	v_mul_f32_e32 v178, v161, v6
	v_mul_f32_e32 v160, 0x3f3504f3, v171
	v_mul_f32_e32 v161, v160, v160
	v_fmamk_f32 v162, v161, 0xba1345e1, v8
	v_fmaak_f32 v162, v161, v162, 0xbcdac9b8
	v_fmaak_f32 v162, v161, v162, 0x3de703be
	v_fmaak_f32 v162, v161, v162, 0xbec09330
	v_fmaak_f32 v161, v161, v162, 0x3e0375d0
	v_fma_f32 v165, |v160|, v161, |v160|
	v_fma_f32 v161, |v160|, s72, v9
	v_fma_f32 v161, |v160|, v161, s73
	v_fma_f32 v161, |v160|, v161, s74
	v_fma_f32 v161, |v160|, v161, s75
	v_fma_f32 v161, |v160|, v161, s76
	v_fma_f32 v161, |v160|, v161, s77
	v_fma_f32 v161, |v160|, v161, |v160|
	v_mul_f32_e32 v162, 0xbfb8aa3b, v161
	v_fma_f32 v163, v161, s78, -v162
	v_rndne_f32_e32 v164, v162
	v_fmac_f32_e32 v163, 0xb2a5705f, v161
	v_sub_f32_e32 v162, v162, v164
	v_add_f32_e32 v162, v162, v163
	v_cvt_i32_f32_e32 v163, v164
	v_exp_f32_e32 v162, v162
	v_cmp_nlt_f32_e32 vcc, s79, v161
	v_ldexp_f32 v162, v162, v163
	s_nop 0
	v_cndmask_b32_e32 v162, 0, v162, vcc
	v_cmp_ngt_f32_e32 vcc, s80, v161
	s_nop 1
	v_cndmask_b32_e32 v161, v3, v162, vcc
	v_sub_f32_e32 v166, 1.0, v161
	v_cmp_lt_f32_e64 vcc, |v160|, 1.0
	s_nop 1
	v_cndmask_b32_e32 v165, v166, v165, vcc
	v_bfi_b32 v165, s81, v165, v160
	v_mul_f32_e32 v161, 0.5, v171
	v_add_f32_e32 v165, 1.0, v165
	v_mul_f32_e32 v161, v161, v165
	v_mul_f32_e32 v179, v161, v7
	v_cvt_pk_bf16_f32 v180, v176, v177
	v_cvt_pk_bf16_f32 v181, v178, v179
	global_store_dwordx2 v2, v[180:181], s[34:35]
	s_add_u32 s34, s34, 0x800
	s_addc_u32 s35, s35, 0
	s_waitcnt vmcnt(11)
	v_fma_f32 v4, v130, v4, v134
	v_fma_f32 v5, v131, v5, v135
	v_fma_f32 v6, v132, v6, v136
	v_fma_f32 v7, v133, v7, v137
	v_lshlrev_b32_e32 v168, 16, v138
	v_and_b32_e32 v169, 0xffff0000, v138
	v_lshlrev_b32_e32 v170, 16, v139
	v_and_b32_e32 v171, 0xffff0000, v139
	v_mul_f32_e32 v160, 0x3f3504f3, v168
	v_mul_f32_e32 v161, v160, v160
	v_fmamk_f32 v162, v161, 0xba1345e1, v8
	v_fmaak_f32 v162, v161, v162, 0xbcdac9b8
	v_fmaak_f32 v162, v161, v162, 0x3de703be
	v_fmaak_f32 v162, v161, v162, 0xbec09330
	v_fmaak_f32 v161, v161, v162, 0x3e0375d0
	v_fma_f32 v165, |v160|, v161, |v160|
	v_fma_f32 v161, |v160|, s72, v9
	v_fma_f32 v161, |v160|, v161, s73
	v_fma_f32 v161, |v160|, v161, s74
	v_fma_f32 v161, |v160|, v161, s75
	v_fma_f32 v161, |v160|, v161, s76
	v_fma_f32 v161, |v160|, v161, s77
	v_fma_f32 v161, |v160|, v161, |v160|
	v_mul_f32_e32 v162, 0xbfb8aa3b, v161
	v_fma_f32 v163, v161, s78, -v162
	v_rndne_f32_e32 v164, v162
	v_fmac_f32_e32 v163, 0xb2a5705f, v161
	v_sub_f32_e32 v162, v162, v164
	v_add_f32_e32 v162, v162, v163
	v_cvt_i32_f32_e32 v163, v164
	v_exp_f32_e32 v162, v162
	v_cmp_nlt_f32_e32 vcc, s79, v161
	v_ldexp_f32 v162, v162, v163
	s_nop 0
	v_cndmask_b32_e32 v162, 0, v162, vcc
	v_cmp_ngt_f32_e32 vcc, s80, v161
	s_nop 1
	v_cndmask_b32_e32 v161, v3, v162, vcc
	v_sub_f32_e32 v166, 1.0, v161
	v_cmp_lt_f32_e64 vcc, |v160|, 1.0
	s_nop 1
	v_cndmask_b32_e32 v165, v166, v165, vcc
	v_bfi_b32 v165, s81, v165, v160
	v_mul_f32_e32 v161, 0.5, v168
	v_add_f32_e32 v165, 1.0, v165
	v_mul_f32_e32 v161, v161, v165
	v_mul_f32_e32 v176, v161, v4
	v_mul_f32_e32 v160, 0x3f3504f3, v169
	v_mul_f32_e32 v161, v160, v160
	v_fmamk_f32 v162, v161, 0xba1345e1, v8
	v_fmaak_f32 v162, v161, v162, 0xbcdac9b8
	v_fmaak_f32 v162, v161, v162, 0x3de703be
	v_fmaak_f32 v162, v161, v162, 0xbec09330
	v_fmaak_f32 v161, v161, v162, 0x3e0375d0
	v_fma_f32 v165, |v160|, v161, |v160|
	v_fma_f32 v161, |v160|, s72, v9
	v_fma_f32 v161, |v160|, v161, s73
	v_fma_f32 v161, |v160|, v161, s74
	v_fma_f32 v161, |v160|, v161, s75
	v_fma_f32 v161, |v160|, v161, s76
	v_fma_f32 v161, |v160|, v161, s77
	v_fma_f32 v161, |v160|, v161, |v160|
	v_mul_f32_e32 v162, 0xbfb8aa3b, v161
	v_fma_f32 v163, v161, s78, -v162
	v_rndne_f32_e32 v164, v162
	v_fmac_f32_e32 v163, 0xb2a5705f, v161
	v_sub_f32_e32 v162, v162, v164
	v_add_f32_e32 v162, v162, v163
	v_cvt_i32_f32_e32 v163, v164
	v_exp_f32_e32 v162, v162
	v_cmp_nlt_f32_e32 vcc, s79, v161
	v_ldexp_f32 v162, v162, v163
	s_nop 0
	v_cndmask_b32_e32 v162, 0, v162, vcc
	v_cmp_ngt_f32_e32 vcc, s80, v161
	s_nop 1
	v_cndmask_b32_e32 v161, v3, v162, vcc
	v_sub_f32_e32 v166, 1.0, v161
	v_cmp_lt_f32_e64 vcc, |v160|, 1.0
	s_nop 1
	v_cndmask_b32_e32 v165, v166, v165, vcc
	v_bfi_b32 v165, s81, v165, v160
	v_mul_f32_e32 v161, 0.5, v169
	v_add_f32_e32 v165, 1.0, v165
	v_mul_f32_e32 v161, v161, v165
	v_mul_f32_e32 v177, v161, v5
	v_mul_f32_e32 v160, 0x3f3504f3, v170
	v_mul_f32_e32 v161, v160, v160
	v_fmamk_f32 v162, v161, 0xba1345e1, v8
	v_fmaak_f32 v162, v161, v162, 0xbcdac9b8
	v_fmaak_f32 v162, v161, v162, 0x3de703be
	v_fmaak_f32 v162, v161, v162, 0xbec09330
	v_fmaak_f32 v161, v161, v162, 0x3e0375d0
	v_fma_f32 v165, |v160|, v161, |v160|
	v_fma_f32 v161, |v160|, s72, v9
	v_fma_f32 v161, |v160|, v161, s73
	v_fma_f32 v161, |v160|, v161, s74
	v_fma_f32 v161, |v160|, v161, s75
	v_fma_f32 v161, |v160|, v161, s76
; DEV unsigned pack2(float a, float b) { float2v v = {a, b}; return __builtin_bit_cast(unsigned, __builtin_convertvector(v, bf16x2v)); }
; DEV float bflo(unsigned u) { return __uint_as_float(u << 16); }
; DEV float bfhi(unsigned u) { return __uint_as_float(u & 0xffff0000u); }
; DEV float gelu_exact(float v) { return 0.5f * v * (1.f + erff(v * 0.7071067811865476f)); }
; DEV void ph_scan2(const Params& p, int item) {
;     ...
; #pragma unroll 8
;   for (int t = 0; t < CHL; ++t) {
;     float4 a = *(const float4*)(p.a_arr + (row0 + t) * 1024 + ch);
;     float4 bb = *(const float4*)(p.b_arr + (row0 + t) * 1024 + ch);
;     u32x2 xg = *(const u32x2*)(p.z + (row0 + t) * ZLD + CXG + ch);
;     H[0] = a.x * H[0] + bb.x; H[1] = a.y * H[1] + bb.y; H[2] = a.z * H[2] + bb.z; H[3] = a.w * H[3] + bb.w;
;     u32x2 pk;
;     pk[0] = pack2(gelu_exact(bflo(xg[0])) * H[0], gelu_exact(bfhi(xg[0])) * H[1]);
;     pk[1] = pack2(gelu_exact(bflo(xg[1])) * H[2], gelu_exact(bfhi(xg[1])) * H[3]);
;     *(u32x2*)(p.orn + (row0 + t) * 1024 + ch) = pk;
;   }
	v_fma_f32 v161, |v160|, v161, s77
	v_fma_f32 v161, |v160|, v161, |v160|
	v_mul_f32_e32 v162, 0xbfb8aa3b, v161
	v_fma_f32 v163, v161, s78, -v162
	v_rndne_f32_e32 v164, v162
	v_fmac_f32_e32 v163, 0xb2a5705f, v161
	v_sub_f32_e32 v162, v162, v164
	v_add_f32_e32 v162, v162, v163
	v_cvt_i32_f32_e32 v163, v164
	v_exp_f32_e32 v162, v162
	v_cmp_nlt_f32_e32 vcc, s79, v161
	v_ldexp_f32 v162, v162, v163
	s_nop 0
	v_cndmask_b32_e32 v162, 0, v162, vcc
	v_cmp_ngt_f32_e32 vcc, s80, v161
	s_nop 1
	v_cndmask_b32_e32 v161, v3, v162, vcc
	v_sub_f32_e32 v166, 1.0, v161
	v_cmp_lt_f32_e64 vcc, |v160|, 1.0
	s_nop 1
	v_cndmask_b32_e32 v165, v166, v165, vcc
	v_bfi_b32 v165, s81, v165, v160
	v_mul_f32_e32 v161, 0.5, v170
	v_add_f32_e32 v165, 1.0, v165
	v_mul_f32_e32 v161, v161, v165
	v_mul_f32_e32 v178, v161, v6
	v_mul_f32_e32 v160, 0x3f3504f3, v171
	v_mul_f32_e32 v161, v160, v160
	v_fmamk_f32 v162, v161, 0xba1345e1, v8
	v_fmaak_f32 v162, v161, v162, 0xbcdac9b8
	v_fmaak_f32 v162, v161, v162, 0x3de703be
	v_fmaak_f32 v162, v161, v162, 0xbec09330
	v_fmaak_f32 v161, v161, v162, 0x3e0375d0
	v_fma_f32 v165, |v160|, v161, |v160|
	v_fma_f32 v161, |v160|, s72, v9
	v_fma_f32 v161, |v160|, v161, s73
	v_fma_f32 v161, |v160|, v161, s74
	v_fma_f32 v161, |v160|, v161, s75
	v_fma_f32 v161, |v160|, v161, s76
	v_fma_f32 v161, |v160|, v161, s77
	v_fma_f32 v161, |v160|, v161, |v160|
	v_mul_f32_e32 v162, 0xbfb8aa3b, v161
	v_fma_f32 v163, v161, s78, -v162
	v_rndne_f32_e32 v164, v162
	v_fmac_f32_e32 v163, 0xb2a5705f, v161
	v_sub_f32_e32 v162, v162, v164
	v_add_f32_e32 v162, v162, v163
	v_cvt_i32_f32_e32 v163, v164
	v_exp_f32_e32 v162, v162
	v_cmp_nlt_f32_e32 vcc, s79, v161
	v_ldexp_f32 v162, v162, v163
	s_nop 0
	v_cndmask_b32_e32 v162, 0, v162, vcc
	v_cmp_ngt_f32_e32 vcc, s80, v161
	s_nop 1
	v_cndmask_b32_e32 v161, v3, v162, vcc
	v_sub_f32_e32 v166, 1.0, v161
	v_cmp_lt_f32_e64 vcc, |v160|, 1.0
	s_nop 1
	v_cndmask_b32_e32 v165, v166, v165, vcc
	v_bfi_b32 v165, s81, v165, v160
	v_mul_f32_e32 v161, 0.5, v171
	v_add_f32_e32 v165, 1.0, v165
	v_mul_f32_e32 v161, v161, v165
	v_mul_f32_e32 v179, v161, v7
	v_cvt_pk_bf16_f32 v180, v176, v177
	v_cvt_pk_bf16_f32 v181, v178, v179
	global_store_dwordx2 v2, v[180:181], s[34:35]
	s_add_u32 s34, s34, 0x800
	s_addc_u32 s35, s35, 0
	s_waitcnt vmcnt(9)
	v_fma_f32 v4, v140, v4, v144
	v_fma_f32 v5, v141, v5, v145
	v_fma_f32 v6, v142, v6, v146
	v_fma_f32 v7, v143, v7, v147
	v_lshlrev_b32_e32 v168, 16, v148
	v_and_b32_e32 v169, 0xffff0000, v148
	v_lshlrev_b32_e32 v170, 16, v149
	v_and_b32_e32 v171, 0xffff0000, v149
	v_mul_f32_e32 v160, 0x3f3504f3, v168
	v_mul_f32_e32 v161, v160, v160
	v_fmamk_f32 v162, v161, 0xba1345e1, v8
	v_fmaak_f32 v162, v161, v162, 0xbcdac9b8
	v_fmaak_f32 v162, v161, v162, 0x3de703be
	v_fmaak_f32 v162, v161, v162, 0xbec09330
	v_fmaak_f32 v161, v161, v162, 0x3e0375d0
	v_fma_f32 v165, |v160|, v161, |v160|
	v_fma_f32 v161, |v160|, s72, v9
	v_fma_f32 v161, |v160|, v161, s73
	v_fma_f32 v161, |v160|, v161, s74
	v_fma_f32 v161, |v160|, v161, s75
	v_fma_f32 v161, |v160|, v161, s76
	v_fma_f32 v161, |v160|, v161, s77
	v_fma_f32 v161, |v160|, v161, |v160|
	v_mul_f32_e32 v162, 0xbfb8aa3b, v161
	v_fma_f32 v163, v161, s78, -v162
	v_rndne_f32_e32 v164, v162
	v_fmac_f32_e32 v163, 0xb2a5705f, v161
	v_sub_f32_e32 v162, v162, v164
	v_add_f32_e32 v162, v162, v163
	v_cvt_i32_f32_e32 v163, v164
	v_exp_f32_e32 v162, v162
	v_cmp_nlt_f32_e32 vcc, s79, v161
	v_ldexp_f32 v162, v162, v163
	s_nop 0
	v_cndmask_b32_e32 v162, 0, v162, vcc
	v_cmp_ngt_f32_e32 vcc, s80, v161
	s_nop 1
	v_cndmask_b32_e32 v161, v3, v162, vcc
	v_sub_f32_e32 v166, 1.0, v161
	v_cmp_lt_f32_e64 vcc, |v160|, 1.0
	s_nop 1
	v_cndmask_b32_e32 v165, v166, v165, vcc
	v_bfi_b32 v165, s81, v165, v160
	v_mul_f32_e32 v161, 0.5, v168
	v_add_f32_e32 v165, 1.0, v165
	v_mul_f32_e32 v161, v161, v165
	v_mul_f32_e32 v176, v161, v4
	v_mul_f32_e32 v160, 0x3f3504f3, v169
	v_mul_f32_e32 v161, v160, v160
	v_fmamk_f32 v162, v161, 0xba1345e1, v8
	v_fmaak_f32 v162, v161, v162, 0xbcdac9b8
	v_fmaak_f32 v162, v161, v162, 0x3de703be
	v_fmaak_f32 v162, v161, v162, 0xbec09330
	v_fmaak_f32 v161, v161, v162, 0x3e0375d0
	v_fma_f32 v165, |v160|, v161, |v160|
	v_fma_f32 v161, |v160|, s72, v9
	v_fma_f32 v161, |v160|, v161, s73
	v_fma_f32 v161, |v160|, v161, s74
	v_fma_f32 v161, |v160|, v161, s75
	v_fma_f32 v161, |v160|, v161, s76
	v_fma_f32 v161, |v160|, v161, s77
	v_fma_f32 v161, |v160|, v161, |v160|
	v_mul_f32_e32 v162, 0xbfb8aa3b, v161
	v_fma_f32 v163, v161, s78, -v162
	v_rndne_f32_e32 v164, v162
	v_fmac_f32_e32 v163, 0xb2a5705f, v161
	v_sub_f32_e32 v162, v162, v164
	v_add_f32_e32 v162, v162, v163
	v_cvt_i32_f32_e32 v163, v164
	v_exp_f32_e32 v162, v162
	v_cmp_nlt_f32_e32 vcc, s79, v161
	v_ldexp_f32 v162, v162, v163
	s_nop 0
	v_cndmask_b32_e32 v162, 0, v162, vcc
	v_cmp_ngt_f32_e32 vcc, s80, v161
	s_nop 1
	v_cndmask_b32_e32 v161, v3, v162, vcc
	v_sub_f32_e32 v166, 1.0, v161
	v_cmp_lt_f32_e64 vcc, |v160|, 1.0
	s_nop 1
	v_cndmask_b32_e32 v165, v166, v165, vcc
	v_bfi_b32 v165, s81, v165, v160
	v_mul_f32_e32 v161, 0.5, v169
	v_add_f32_e32 v165, 1.0, v165
	v_mul_f32_e32 v161, v161, v165
	v_mul_f32_e32 v177, v161, v5
	v_mul_f32_e32 v160, 0x3f3504f3, v170
	v_mul_f32_e32 v161, v160, v160
	v_fmamk_f32 v162, v161, 0xba1345e1, v8
	v_fmaak_f32 v162, v161, v162, 0xbcdac9b8
	v_fmaak_f32 v162, v161, v162, 0x3de703be
	v_fmaak_f32 v162, v161, v162, 0xbec09330
	v_fmaak_f32 v161, v161, v162, 0x3e0375d0
	v_fma_f32 v165, |v160|, v161, |v160|
	v_fma_f32 v161, |v160|, s72, v9
	v_fma_f32 v161, |v160|, v161, s73
	v_fma_f32 v161, |v160|, v161, s74
	v_fma_f32 v161, |v160|, v161, s75
	v_fma_f32 v161, |v160|, v161, s76
	v_fma_f32 v161, |v160|, v161, s77
; DEV unsigned pack2(float a, float b) { float2v v = {a, b}; return __builtin_bit_cast(unsigned, __builtin_convertvector(v, bf16x2v)); }
; DEV float bflo(unsigned u) { return __uint_as_float(u << 16); }
; DEV float bfhi(unsigned u) { return __uint_as_float(u & 0xffff0000u); }
; DEV float gelu_exact(float v) { return 0.5f * v * (1.f + erff(v * 0.7071067811865476f)); }
; DEV void ph_scan2(const Params& p, int item) {
;     ...
; #pragma unroll 8
;   for (int t = 0; t < CHL; ++t) {
;     float4 a = *(const float4*)(p.a_arr + (row0 + t) * 1024 + ch);
;     float4 bb = *(const float4*)(p.b_arr + (row0 + t) * 1024 + ch);
;     u32x2 xg = *(const u32x2*)(p.z + (row0 + t) * ZLD + CXG + ch);
;     H[0] = a.x * H[0] + bb.x; H[1] = a.y * H[1] + bb.y; H[2] = a.z * H[2] + bb.z; H[3] = a.w * H[3] + bb.w;
;     u32x2 pk;
;     pk[0] = pack2(gelu_exact(bflo(xg[0])) * H[0], gelu_exact(bfhi(xg[0])) * H[1]);
;     pk[1] = pack2(gelu_exact(bflo(xg[1])) * H[2], gelu_exact(bfhi(xg[1])) * H[3]);
;     *(u32x2*)(p.orn + (row0 + t) * 1024 + ch) = pk;
;   }
	v_fma_f32 v161, |v160|, v161, |v160|
	v_mul_f32_e32 v162, 0xbfb8aa3b, v161
	v_fma_f32 v163, v161, s78, -v162
	v_rndne_f32_e32 v164, v162
	v_fmac_f32_e32 v163, 0xb2a5705f, v161
	v_sub_f32_e32 v162, v162, v164
	v_add_f32_e32 v162, v162, v163
	v_cvt_i32_f32_e32 v163, v164
	v_exp_f32_e32 v162, v162
	v_cmp_nlt_f32_e32 vcc, s79, v161
	v_ldexp_f32 v162, v162, v163
	s_nop 0
	v_cndmask_b32_e32 v162, 0, v162, vcc
	v_cmp_ngt_f32_e32 vcc, s80, v161
	s_nop 1
	v_cndmask_b32_e32 v161, v3, v162, vcc
	v_sub_f32_e32 v166, 1.0, v161
	v_cmp_lt_f32_e64 vcc, |v160|, 1.0
	s_nop 1
	v_cndmask_b32_e32 v165, v166, v165, vcc
	v_bfi_b32 v165, s81, v165, v160
	v_mul_f32_e32 v161, 0.5, v170
	v_add_f32_e32 v165, 1.0, v165
	v_mul_f32_e32 v161, v161, v165
	v_mul_f32_e32 v178, v161, v6
	v_mul_f32_e32 v160, 0x3f3504f3, v171
	v_mul_f32_e32 v161, v160, v160
	v_fmamk_f32 v162, v161, 0xba1345e1, v8
	v_fmaak_f32 v162, v161, v162, 0xbcdac9b8
	v_fmaak_f32 v162, v161, v162, 0x3de703be
	v_fmaak_f32 v162, v161, v162, 0xbec09330
	v_fmaak_f32 v161, v161, v162, 0x3e0375d0
	v_fma_f32 v165, |v160|, v161, |v160|
	v_fma_f32 v161, |v160|, s72, v9
	v_fma_f32 v161, |v160|, v161, s73
	v_fma_f32 v161, |v160|, v161, s74
	v_fma_f32 v161, |v160|, v161, s75
	v_fma_f32 v161, |v160|, v161, s76
	v_fma_f32 v161, |v160|, v161, s77
	v_fma_f32 v161, |v160|, v161, |v160|
	v_mul_f32_e32 v162, 0xbfb8aa3b, v161
	v_fma_f32 v163, v161, s78, -v162
	v_rndne_f32_e32 v164, v162
	v_fmac_f32_e32 v163, 0xb2a5705f, v161
	v_sub_f32_e32 v162, v162, v164
	v_add_f32_e32 v162, v162, v163
	v_cvt_i32_f32_e32 v163, v164
	v_exp_f32_e32 v162, v162
	v_cmp_nlt_f32_e32 vcc, s79, v161
	v_ldexp_f32 v162, v162, v163
	s_nop 0
	v_cndmask_b32_e32 v162, 0, v162, vcc
	v_cmp_ngt_f32_e32 vcc, s80, v161
	s_nop 1
	v_cndmask_b32_e32 v161, v3, v162, vcc
	v_sub_f32_e32 v166, 1.0, v161
	v_cmp_lt_f32_e64 vcc, |v160|, 1.0
	s_nop 1
	v_cndmask_b32_e32 v165, v166, v165, vcc
	v_bfi_b32 v165, s81, v165, v160
	v_mul_f32_e32 v161, 0.5, v171
	v_add_f32_e32 v165, 1.0, v165
	v_mul_f32_e32 v161, v161, v165
	v_mul_f32_e32 v179, v161, v7
	v_cvt_pk_bf16_f32 v180, v176, v177
	v_cvt_pk_bf16_f32 v181, v178, v179
	global_store_dwordx2 v2, v[180:181], s[34:35]
	s_add_u32 s34, s34, 0x800
	s_addc_u32 s35, s35, 0
	s_waitcnt vmcnt(7)
; DEV unsigned pack2(float a, float b) { float2v v = {a, b}; return __builtin_bit_cast(unsigned, __builtin_convertvector(v, bf16x2v)); }
; DEV float bflo(unsigned u) { return __uint_as_float(u << 16); }
; DEV float bfhi(unsigned u) { return __uint_as_float(u & 0xffff0000u); }
; DEV float gelu_exact(float v) { return 0.5f * v * (1.f + erff(v * 0.7071067811865476f)); }
; DEV void ph_scan2(const Params& p, int item) {
;     ...
;   for (int t = 0; t < CHL; ++t) {
;     float4 a = *(const float4*)(p.a_arr + (row0 + t) * 1024 + ch);
;     float4 bb = *(const float4*)(p.b_arr + (row0 + t) * 1024 + ch);
;     u32x2 xg = *(const u32x2*)(p.z + (row0 + t) * ZLD + CXG + ch);
;     H[0] = a.x * H[0] + bb.x; H[1] = a.y * H[1] + bb.y; H[2] = a.z * H[2] + bb.z; H[3] = a.w * H[3] + bb.w;
;     u32x2 pk;
;     pk[0] = pack2(gelu_exact(bflo(xg[0])) * H[0], gelu_exact(bfhi(xg[0])) * H[1]);
;     pk[1] = pack2(gelu_exact(bflo(xg[1])) * H[2], gelu_exact(bfhi(xg[1])) * H[3]);
;     *(u32x2*)(p.orn + (row0 + t) * 1024 + ch) = pk;
;   }
	v_fma_f32 v4, v150, v4, v154
	v_fma_f32 v5, v151, v5, v155
	v_fma_f32 v6, v152, v6, v156
	v_fma_f32 v7, v153, v7, v157
	v_lshlrev_b32_e32 v168, 16, v158
	v_and_b32_e32 v169, 0xffff0000, v158
	v_lshlrev_b32_e32 v170, 16, v159
	v_and_b32_e32 v171, 0xffff0000, v159
	v_mul_f32_e32 v160, 0x3f3504f3, v168
	v_mul_f32_e32 v161, v160, v160
	v_fmamk_f32 v162, v161, 0xba1345e1, v8
	v_fmaak_f32 v162, v161, v162, 0xbcdac9b8
	v_fmaak_f32 v162, v161, v162, 0x3de703be
	v_fmaak_f32 v162, v161, v162, 0xbec09330
	v_fmaak_f32 v161, v161, v162, 0x3e0375d0
	v_fma_f32 v165, |v160|, v161, |v160|
	v_fma_f32 v161, |v160|, s72, v9
	v_fma_f32 v161, |v160|, v161, s73
	v_fma_f32 v161, |v160|, v161, s74
	v_fma_f32 v161, |v160|, v161, s75
	v_fma_f32 v161, |v160|, v161, s76
	v_fma_f32 v161, |v160|, v161, s77
	v_fma_f32 v161, |v160|, v161, |v160|
	v_mul_f32_e32 v162, 0xbfb8aa3b, v161
	v_fma_f32 v163, v161, s78, -v162
	v_rndne_f32_e32 v164, v162
	v_fmac_f32_e32 v163, 0xb2a5705f, v161
	v_sub_f32_e32 v162, v162, v164
	v_add_f32_e32 v162, v162, v163
	v_cvt_i32_f32_e32 v163, v164
	v_exp_f32_e32 v162, v162
	v_cmp_nlt_f32_e32 vcc, s79, v161
	v_ldexp_f32 v162, v162, v163
	s_nop 0
	v_cndmask_b32_e32 v162, 0, v162, vcc
	v_cmp_ngt_f32_e32 vcc, s80, v161
	s_nop 1
	v_cndmask_b32_e32 v161, v3, v162, vcc
	v_sub_f32_e32 v166, 1.0, v161
	v_cmp_lt_f32_e64 vcc, |v160|, 1.0
	s_nop 1
	v_cndmask_b32_e32 v165, v166, v165, vcc
	v_bfi_b32 v165, s81, v165, v160
	v_mul_f32_e32 v161, 0.5, v168
	v_add_f32_e32 v165, 1.0, v165
	v_mul_f32_e32 v161, v161, v165
	v_mul_f32_e32 v176, v161, v4
	v_mul_f32_e32 v160, 0x3f3504f3, v169
	v_mul_f32_e32 v161, v160, v160
	v_fmamk_f32 v162, v161, 0xba1345e1, v8
	v_fmaak_f32 v162, v161, v162, 0xbcdac9b8
	v_fmaak_f32 v162, v161, v162, 0x3de703be
	v_fmaak_f32 v162, v161, v162, 0xbec09330
	v_fmaak_f32 v161, v161, v162, 0x3e0375d0
	v_fma_f32 v165, |v160|, v161, |v160|
	v_fma_f32 v161, |v160|, s72, v9
	v_fma_f32 v161, |v160|, v161, s73
	v_fma_f32 v161, |v160|, v161, s74
	v_fma_f32 v161, |v160|, v161, s75
	v_fma_f32 v161, |v160|, v161, s76
	v_fma_f32 v161, |v160|, v161, s77
	v_fma_f32 v161, |v160|, v161, |v160|
	v_mul_f32_e32 v162, 0xbfb8aa3b, v161
	v_fma_f32 v163, v161, s78, -v162
	v_rndne_f32_e32 v164, v162
	v_fmac_f32_e32 v163, 0xb2a5705f, v161
	v_sub_f32_e32 v162, v162, v164
	v_add_f32_e32 v162, v162, v163
	v_cvt_i32_f32_e32 v163, v164
	v_exp_f32_e32 v162, v162
	v_cmp_nlt_f32_e32 vcc, s79, v161
	v_ldexp_f32 v162, v162, v163
	s_nop 0
	v_cndmask_b32_e32 v162, 0, v162, vcc
	v_cmp_ngt_f32_e32 vcc, s80, v161
	s_nop 1
	v_cndmask_b32_e32 v161, v3, v162, vcc
	v_sub_f32_e32 v166, 1.0, v161
	v_cmp_lt_f32_e64 vcc, |v160|, 1.0
	s_nop 1
	v_cndmask_b32_e32 v165, v166, v165, vcc
	v_bfi_b32 v165, s81, v165, v160
	v_mul_f32_e32 v161, 0.5, v169
	v_add_f32_e32 v165, 1.0, v165
	v_mul_f32_e32 v161, v161, v165
	v_mul_f32_e32 v177, v161, v5
	v_mul_f32_e32 v160, 0x3f3504f3, v170
	v_mul_f32_e32 v161, v160, v160
	v_fmamk_f32 v162, v161, 0xba1345e1, v8
	v_fmaak_f32 v162, v161, v162, 0xbcdac9b8
	v_fmaak_f32 v162, v161, v162, 0x3de703be
	v_fmaak_f32 v162, v161, v162, 0xbec09330
	v_fmaak_f32 v161, v161, v162, 0x3e0375d0
	v_fma_f32 v165, |v160|, v161, |v160|
	v_fma_f32 v161, |v160|, s72, v9
	v_fma_f32 v161, |v160|, v161, s73
	v_fma_f32 v161, |v160|, v161, s74
	v_fma_f32 v161, |v160|, v161, s75
	v_fma_f32 v161, |v160|, v161, s76
	v_fma_f32 v161, |v160|, v161, s77
	v_fma_f32 v161, |v160|, v161, |v160|
	v_mul_f32_e32 v162, 0xbfb8aa3b, v161
	v_fma_f32 v163, v161, s78, -v162
	v_rndne_f32_e32 v164, v162
	v_fmac_f32_e32 v163, 0xb2a5705f, v161
	v_sub_f32_e32 v162, v162, v164
	v_add_f32_e32 v162, v162, v163
	v_cvt_i32_f32_e32 v163, v164
	v_exp_f32_e32 v162, v162
	v_cmp_nlt_f32_e32 vcc, s79, v161
	v_ldexp_f32 v162, v162, v163
	s_nop 0
	v_cndmask_b32_e32 v162, 0, v162, vcc
	v_cmp_ngt_f32_e32 vcc, s80, v161
	s_nop 1
	v_cndmask_b32_e32 v161, v3, v162, vcc
	v_sub_f32_e32 v166, 1.0, v161
	v_cmp_lt_f32_e64 vcc, |v160|, 1.0
	s_nop 1
	v_cndmask_b32_e32 v165, v166, v165, vcc
	v_bfi_b32 v165, s81, v165, v160
	v_mul_f32_e32 v161, 0.5, v170
	v_add_f32_e32 v165, 1.0, v165
	v_mul_f32_e32 v161, v161, v165
	v_mul_f32_e32 v178, v161, v6
	v_mul_f32_e32 v160, 0x3f3504f3, v171
	v_mul_f32_e32 v161, v160, v160
	v_fmamk_f32 v162, v161, 0xba1345e1, v8
	v_fmaak_f32 v162, v161, v162, 0xbcdac9b8
	v_fmaak_f32 v162, v161, v162, 0x3de703be
	v_fmaak_f32 v162, v161, v162, 0xbec09330
	v_fmaak_f32 v161, v161, v162, 0x3e0375d0
	v_fma_f32 v165, |v160|, v161, |v160|
	v_fma_f32 v161, |v160|, s72, v9
	v_fma_f32 v161, |v160|, v161, s73
	v_fma_f32 v161, |v160|, v161, s74
	v_fma_f32 v161, |v160|, v161, s75
	v_fma_f32 v161, |v160|, v161, s76
	v_fma_f32 v161, |v160|, v161, s77
	v_fma_f32 v161, |v160|, v161, |v160|
	v_mul_f32_e32 v162, 0xbfb8aa3b, v161
	v_fma_f32 v163, v161, s78, -v162
	v_rndne_f32_e32 v164, v162
	v_fmac_f32_e32 v163, 0xb2a5705f, v161
	v_sub_f32_e32 v162, v162, v164
	v_add_f32_e32 v162, v162, v163
	v_cvt_i32_f32_e32 v163, v164
	v_exp_f32_e32 v162, v162
	v_cmp_nlt_f32_e32 vcc, s79, v161
	v_ldexp_f32 v162, v162, v163
	s_nop 0
	v_cndmask_b32_e32 v162, 0, v162, vcc
	v_cmp_ngt_f32_e32 vcc, s80, v161
	s_nop 1
	v_cndmask_b32_e32 v161, v3, v162, vcc
	v_sub_f32_e32 v166, 1.0, v161
	v_cmp_lt_f32_e64 vcc, |v160|, 1.0
	s_nop 1
	v_cndmask_b32_e32 v165, v166, v165, vcc
	v_bfi_b32 v165, s81, v165, v160
	v_mul_f32_e32 v161, 0.5, v171
	v_add_f32_e32 v165, 1.0, v165
	v_mul_f32_e32 v161, v161, v165
	v_mul_f32_e32 v179, v161, v7
	v_cvt_pk_bf16_f32 v180, v176, v177
	v_cvt_pk_bf16_f32 v181, v178, v179
	global_store_dwordx2 v2, v[180:181], s[34:35]
	s_add_u32 s34, s34, 0x800
	s_addc_u32 s35, s35, 0
	s_add_u32 s41, s41, 1
	s_cmp_lt_u32 s41, 4
	s_cbranch_scc1 .Lsc_main
	s_cmp_gt_u32 s8, 15
	s_cbranch_scc1 .Lsc_end
	s_cmp_lg_u32 s50, s94
	s_cbranch_scc1 .Lsc_end
	s_sub_u32 s9, 31, s8
	s_lshl_b32 s9, s9, 4
	s_and_b32 s50, s94, 15
	s_add_u32 s50, s50, s9
	s_branch .Lsc_item
